# grid barrier: L1 invalidate hoisted before the spin (off critical path); write-through stores in residual epilogue; prologue vmcnt(0)->vmcnt(6)
# speedup vs baseline: 1.0190x; 1.0143x over previous
; __device__ __forceinline__ unsigned xb_ld(unsigned* p)              { return __hip_atomic_load(p, __ATOMIC_RELAXED, __HIP_MEMORY_SCOPE_AGENT); }
; __device__ __forceinline__ unsigned xb_add(unsigned* p, unsigned v) { return __hip_atomic_fetch_add(p, v, __ATOMIC_RELAXED, __HIP_MEMORY_SCOPE_AGENT); }
; #define XB_SPIN(cond, bar) do { unsigned _sp = 0; while (cond) { __builtin_amdgcn_s_sleep(1); \
;     if ((++_sp & 255u) == 0u) { if (xb_ld(&(bar)[XB_TMO])) break; if (_sp > XB_SPIN_CAP) { atomicAdd(&(bar)[XB_TMO], 1u); break; } } } } while (0)
; __device__ __forceinline__ void xcd_barrier(const XcdBarrier& b) {
;     ...
;         const unsigned old = xb_add(&bar[XB_XSUB(b.x)], 1u);
;         const unsigned gen = old / nloc;
;         if (old + 1u == (gen + 1u) * nloc) {
;             __builtin_amdgcn_fence(__ATOMIC_RELEASE, "agent");
;             asm volatile("s_waitcnt vmcnt(0)" ::: "memory");
;             const unsigned og = xb_add(&bar[XB_TOP], 1u);
;             const unsigned tg = og / nx;
;             if (og + 1u == (tg + 1u) * nx) xb_add(&bar[XB_TOPGEN], 1u);
;             else XB_SPIN(xb_ld(&bar[XB_TOPGEN]) == tg, bar);
;             __builtin_amdgcn_fence(__ATOMIC_ACQUIRE, "agent");
;             xb_add(&bar[XB_XGEN(b.x)], 1u);
;             asm volatile("s_waitcnt vmcnt(0)" ::: "memory");
;         } else {
;             XB_SPIN(xb_ld(&bar[XB_XGEN(b.x)]) == gen, bar);
.LBB0_40:
	s_or_b64 exec, exec, s[10:11]
	buffer_inv sc1
	v_cvt_f32_u32_e32 v5, v3
	s_waitcnt vmcnt(0)
	v_readfirstlane_b32 s3, v4
	v_sub_u32_e32 v4, 0, v3
	v_rcp_iflag_f32_e32 v5, v5
	v_add_u32_e32 v6, s3, v2
	v_mul_f32_e32 v5, 0x4f7ffffe, v5
	v_cvt_u32_f32_e32 v5, v5
	v_mul_lo_u32 v2, v4, v5
	v_mul_hi_u32 v2, v5, v2
	v_add_u32_e32 v2, v5, v2
	v_mul_hi_u32 v2, v6, v2
	v_mul_lo_u32 v4, v2, v3
	v_sub_u32_e32 v4, v6, v4
	v_add_u32_e32 v5, 1, v2
	v_sub_u32_e32 v7, v4, v3
	v_cmp_ge_u32_e32 vcc, v4, v3
	s_nop 1
	v_cndmask_b32_e32 v2, v2, v5, vcc
	v_cndmask_b32_e32 v4, v4, v7, vcc
	v_add_u32_e32 v5, 1, v2
	v_cmp_ge_u32_e32 vcc, v4, v3
	v_add_u32_e32 v4, 1, v6
	s_nop 0
	v_cndmask_b32_e32 v2, v2, v5, vcc
	v_mul_lo_u32 v5, v3, v2
	v_add_u32_e32 v3, v5, v3
	v_cmp_ne_u32_e32 vcc, v4, v3
	s_and_saveexec_b64 s[10:11], vcc
	s_xor_b64 s[10:11], exec, s[10:11]
	s_cbranch_execz .LBB0_54
	v_readlane_b32 s14, v252, 10
	v_readlane_b32 s15, v252, 11
	s_waitcnt lgkmcnt(0)
	s_nop 3
	global_load_dword v0, v1, s[14:15] sc1
	s_waitcnt vmcnt(0)
	v_cmp_eq_u32_e32 vcc, v0, v2
	s_and_saveexec_b64 s[16:17], vcc
	s_cbranch_execz .LBB0_53
	s_mov_b32 s3, 1
	s_mov_b64 s[18:19], 0
	s_branch .LBB0_44

; __device__ __forceinline__ unsigned xb_ld(unsigned* p)              { return __hip_atomic_load(p, __ATOMIC_RELAXED, __HIP_MEMORY_SCOPE_AGENT); }
; #define XB_SPIN(cond, bar) do { unsigned _sp = 0; while (cond) { __builtin_amdgcn_s_sleep(1); \
;     if ((++_sp & 255u) == 0u) { if (xb_ld(&(bar)[XB_TMO])) break; if (_sp > XB_SPIN_CAP) { atomicAdd(&(bar)[XB_TMO], 1u); break; } } } } while (0)
; __device__ __forceinline__ void xcd_barrier(const XcdBarrier& b) {
;     ...
;             XB_SPIN(xb_ld(&bar[XB_XGEN(b.x)]) == gen, bar);
;             __builtin_amdgcn_fence(__ATOMIC_ACQUIRE, "agent");
;             asm volatile("s_waitcnt vmcnt(0)" ::: "memory");
.LBB0_53:
	s_or_b64 exec, exec, s[16:17]
	s_waitcnt vmcnt(0)
	s_waitcnt vmcnt(0)

; __device__ __forceinline__ unsigned xb_ld(unsigned* p)              { return __hip_atomic_load(p, __ATOMIC_RELAXED, __HIP_MEMORY_SCOPE_AGENT); }
; __device__ __forceinline__ unsigned xb_add(unsigned* p, unsigned v) { return __hip_atomic_fetch_add(p, v, __ATOMIC_RELAXED, __HIP_MEMORY_SCOPE_AGENT); }
; #define XB_SPIN(cond, bar) do { unsigned _sp = 0; while (cond) { __builtin_amdgcn_s_sleep(1); \
;     if ((++_sp & 255u) == 0u) { if (xb_ld(&(bar)[XB_TMO])) break; if (_sp > XB_SPIN_CAP) { atomicAdd(&(bar)[XB_TMO], 1u); break; } } } } while (0)
; __device__ __forceinline__ void xcd_barrier(const XcdBarrier& b) {
;     ...
;             const unsigned og = xb_add(&bar[XB_TOP], 1u);
;             const unsigned tg = og / nx;
;             if (og + 1u == (tg + 1u) * nx) xb_add(&bar[XB_TOPGEN], 1u);
;             else XB_SPIN(xb_ld(&bar[XB_TOPGEN]) == tg, bar);
;             __builtin_amdgcn_fence(__ATOMIC_ACQUIRE, "agent");
;             xb_add(&bar[XB_XGEN(b.x)], 1u);
;             asm volatile("s_waitcnt vmcnt(0)" ::: "memory");
.LBB0_71:
	s_or_b64 exec, exec, s[10:11]
	s_mov_b64 s[10:11], exec
	v_mbcnt_lo_u32_b32 v0, s10, 0
	v_mbcnt_hi_u32_b32 v0, s11, v0
	v_cmp_eq_u32_e32 vcc, 0, v0
	s_waitcnt vmcnt(0)
	s_and_saveexec_b64 s[16:17], vcc
	s_cbranch_execz .LBB0_73
	s_bcnt1_i32_b64 s3, s[10:11]
	v_readlane_b32 s10, v252, 10
	v_mov_b32_e32 v0, s3
	v_readlane_b32 s11, v252, 11
	s_nop 4
	global_atomic_add v1, v0, s[10:11]

; #define PG8_STAGE(bufoff, gbase, voff) do { _Pragma("unroll") for (int _i = 0; _i < 2; ++_i) \
;         __builtin_amdgcn_global_load_lds((const unsigned*)((const char*)(gbase) + (voff)[_i]), (PG8_LAS unsigned*)(lds + (bufoff) + ldsw + _i * 8192), 16, 0, 0); } while (0)
; #define PG8_WAIT_V(n) asm volatile("s_waitcnt vmcnt(" #n ")" ::: "memory")
; #define PG8_BAR __builtin_amdgcn_s_barrier()
; template <class Epi, class Sched, bool ALIGN_EPI = false, bool SP2 = false>
; __device__ __forceinline__ void gemm_phase(PG8_LAS unsigned char* lds, const Gemm g, const Sched S, const Epi E) {
;     ...
;         PG8_STAGE(PG8_SB(0, 0), cB, voffB); PG8_STAGE(PG8_SB(0, 1), cB + hstep, voffB); PG8_STAGE(PG8_SA(0, 0), cA, voffA); PG8_STAGE(PG8_SA(0, 1), cA + hstep, voffA);
;         if (wr == 1) PG8_BAR;
;         PG8_WAIT_V(2); PG8_BAR;
;         PG8_STAGE(PG8_SB(1, 0), cB + kstep, voffB); PG8_STAGE(PG8_SA(1, 0), cA + kstep, voffA); PG8_STAGE(PG8_SB(1, 1), cB + hstep + kstep, voffB);
;         PG8_WAIT_V(6); PG8_BAR;
;     __device__ __forceinline__ void settle(f32x4 (&acc)[2][2][4][2]) const {
;     ...
;                     if (!Xin32) { const u32x4 h = __builtin_bit_cast(u32x4, acc[a][b][m][0]), l = __builtin_bit_cast(u32x4, acc[a][b][m][1]);
;                         acc[a][b][m][0] = (f32x4){bflo(h.x) + bflo(l.x), bfhi(h.x) + bfhi(l.x), bflo(h.y) + bflo(l.y), bfhi(h.y) + bfhi(l.y)};
;                         acc[a][b][m][1] = (f32x4){bflo(h.z) + bflo(l.z), bfhi(h.z) + bfhi(l.z), bflo(h.w) + bflo(l.w), bfhi(h.w) + bfhi(l.w)}; } }
.LBB0_374:
	v_mov_b32_e32 v149, v1
	v_lshl_add_u64 v[138:139], s[66:67], 0, v[148:149]
	v_mov_b32_e32 v153, v1
	v_lshl_add_u64 v[140:141], s[66:67], 0, v[152:153]
	v_mov_b32_e32 v147, v1
	s_add_i32 m0, s80, 0x18000
	v_lshl_add_u64 v[138:139], v[138:139], 0, s[12:13]
	v_lshl_add_u64 v[154:155], s[68:69], 0, v[146:147]
	v_mov_b32_e32 v151, v1
	s_waitcnt vmcnt(2)
	s_barrier
	global_load_lds_dwordx4 v[138:139], off
	v_lshl_add_u64 v[138:139], v[140:141], 0, s[12:13]
	s_add_i32 m0, s80, 0x1a000
	s_add_i32 s84, s80, 0x8000
	v_lshl_add_u64 v[156:157], s[68:69], 0, v[150:151]
	global_load_lds_dwordx4 v[138:139], off
	v_lshl_add_u64 v[138:139], v[154:155], 0, s[12:13]
	s_mov_b32 m0, s84
	s_add_i32 s85, s80, 0xa000
	v_lshl_add_u64 v[142:143], s[0:1], 0, v[148:149]
	global_load_lds_dwordx4 v[138:139], off
	v_lshl_add_u64 v[138:139], v[156:157], 0, s[12:13]
	s_mov_b32 m0, s85
	v_lshl_add_u64 v[144:145], s[0:1], 0, v[152:153]
	global_load_lds_dwordx4 v[138:139], off
	s_add_i32 m0, s80, 0x1c000
	v_lshl_add_u64 v[138:139], v[142:143], 0, s[12:13]
	global_load_lds_dwordx4 v[138:139], off
	v_lshl_add_u64 v[138:139], v[144:145], 0, s[12:13]
	s_add_i32 m0, s80, 0x1e000
	s_andn2_b64 vcc, exec, s[36:37]
	global_load_lds_dwordx4 v[138:139], off
	s_waitcnt vmcnt(6)
	v_cndmask_b32_e64 v138, 0, 1, s[36:37]
	v_cmp_ne_u32_e64 s[38:39], 1, v138
	s_barrier
	s_waitcnt vmcnt(6)
	s_cbranch_vccnz .LBB0_376
	v_lshlrev_b32_e32 v138, 16, v58
	v_and_b32_e32 v139, 0xffff0000, v58
	v_lshlrev_b32_e32 v142, 16, v50
	v_and_b32_e32 v143, 0xffff0000, v50
	v_lshlrev_b32_e32 v50, 16, v59
	v_lshlrev_b32_e32 v140, 16, v51
	v_and_b32_e32 v141, 0xffff0000, v51
	v_and_b32_e32 v51, 0xffff0000, v59
	v_pk_add_f32 v[140:141], v[50:51], v[140:141]
	v_pk_add_f32 v[138:139], v[138:139], v[142:143]
	v_lshlrev_b32_e32 v50, 16, v60
	v_and_b32_e32 v51, 0xffff0000, v60
	v_lshlrev_b32_e32 v58, 16, v52
	v_and_b32_e32 v59, 0xffff0000, v52
	v_lshlrev_b32_e32 v52, 16, v61
	v_lshlrev_b32_e32 v142, 16, v53
	v_and_b32_e32 v143, 0xffff0000, v53
	v_and_b32_e32 v53, 0xffff0000, v61
	v_pk_add_f32 v[50:51], v[50:51], v[58:59]
	v_mov_b64_e32 v[58:59], v[138:139]
	v_pk_add_f32 v[52:53], v[52:53], v[142:143]
	v_mov_b64_e32 v[60:61], v[140:141]

; #define PG8_STAGE(bufoff, gbase, voff) do { _Pragma("unroll") for (int _i = 0; _i < 2; ++_i) \
;         __builtin_amdgcn_global_load_lds((const unsigned*)((const char*)(gbase) + (voff)[_i]), (PG8_LAS unsigned*)(lds + (bufoff) + ldsw + _i * 8192), 16, 0, 0); } while (0)
; #define PG8_WAIT_V(n) asm volatile("s_waitcnt vmcnt(" #n ")" ::: "memory")
; #define PG8_BAR __builtin_amdgcn_s_barrier()
; template <class Epi, class Sched, bool ALIGN_EPI = false, bool SP2 = false>
; __device__ __forceinline__ void gemm_phase(PG8_LAS unsigned char* lds, const Gemm g, const Sched S, const Epi E) {
;     ...
;         PG8_STAGE(PG8_SB(0, 0), cB, voffB); PG8_STAGE(PG8_SB(0, 1), cB + hstep, voffB); PG8_STAGE(PG8_SA(0, 0), cA, voffA); PG8_STAGE(PG8_SA(0, 1), cA + hstep, voffA);
;         if (wr == 1) PG8_BAR;
;         PG8_WAIT_V(2); PG8_BAR;
;         PG8_STAGE(PG8_SB(1, 0), cB + kstep, voffB); PG8_STAGE(PG8_SA(1, 0), cA + kstep, voffA); PG8_STAGE(PG8_SB(1, 1), cB + hstep + kstep, voffB);
;         PG8_WAIT_V(6); PG8_BAR;
;     __device__ __forceinline__ void settle(f32x4 (&acc)[2][2][4][2]) const {
;     ...
;                     if (!Xin32) { const u32x4 h = __builtin_bit_cast(u32x4, acc[a][b][m][0]), l = __builtin_bit_cast(u32x4, acc[a][b][m][1]);
;                         acc[a][b][m][0] = (f32x4){bflo(h.x) + bflo(l.x), bfhi(h.x) + bfhi(l.x), bflo(h.y) + bflo(l.y), bfhi(h.y) + bfhi(l.y)};
;                         acc[a][b][m][1] = (f32x4){bflo(h.z) + bflo(l.z), bfhi(h.z) + bfhi(l.z), bflo(h.w) + bflo(l.w), bfhi(h.w) + bfhi(l.w)}; } }
.LBB0_496:
	v_lshl_add_u64 v[146:147], s[66:67], 0, v[0:1]
	v_mov_b32_e32 v135, v1
	v_lshl_add_u64 v[148:149], s[66:67], 0, v[134:135]
	v_mov_b32_e32 v131, v1
	s_add_i32 m0, s72, 0x18000
	v_lshl_add_u64 v[146:147], v[146:147], 0, s[12:13]
	v_lshl_add_u64 v[156:157], s[68:69], 0, v[130:131]
	v_mov_b32_e32 v133, v1
	s_waitcnt vmcnt(2)
	s_barrier
	global_load_lds_dwordx4 v[146:147], off
	v_lshl_add_u64 v[146:147], v[148:149], 0, s[12:13]
	s_add_i32 m0, s72, 0x1a000
	s_add_i32 s77, s72, 0x8000
	v_lshl_add_u64 v[158:159], s[68:69], 0, v[132:133]
	global_load_lds_dwordx4 v[146:147], off
	v_lshl_add_u64 v[146:147], v[156:157], 0, s[12:13]
	s_mov_b32 m0, s77
	s_add_i32 s78, s72, 0xa000
	v_lshl_add_u64 v[152:153], s[0:1], 0, v[0:1]
	global_load_lds_dwordx4 v[146:147], off
	v_lshl_add_u64 v[146:147], v[158:159], 0, s[12:13]
	s_mov_b32 m0, s78
	v_lshl_add_u64 v[154:155], s[0:1], 0, v[134:135]
	global_load_lds_dwordx4 v[146:147], off
	s_add_i32 m0, s72, 0x1c000
	v_lshl_add_u64 v[146:147], v[152:153], 0, s[12:13]
	global_load_lds_dwordx4 v[146:147], off
	v_lshl_add_u64 v[146:147], v[154:155], 0, s[12:13]
	s_add_i32 m0, s72, 0x1e000
	v_cndmask_b32_e64 v145, 0, 1, s[36:37]
	global_load_lds_dwordx4 v[146:147], off
	s_waitcnt vmcnt(6)
	v_cmp_ne_u32_e64 s[38:39], 1, v145
	s_andn2_b64 vcc, exec, s[36:37]
	s_barrier
	s_waitcnt vmcnt(6)
	s_cbranch_vccnz .LBB0_498
	v_lshlrev_b32_e32 v146, 16, v62
	v_and_b32_e32 v147, 0xffff0000, v62
	v_lshlrev_b32_e32 v152, 16, v54
	v_and_b32_e32 v153, 0xffff0000, v54
	v_lshlrev_b32_e32 v54, 16, v63
	v_lshlrev_b32_e32 v148, 16, v55
	v_and_b32_e32 v149, 0xffff0000, v55
	v_and_b32_e32 v55, 0xffff0000, v63
	v_pk_add_f32 v[148:149], v[54:55], v[148:149]
	v_pk_add_f32 v[146:147], v[146:147], v[152:153]
	v_lshlrev_b32_e32 v54, 16, v64
	v_and_b32_e32 v55, 0xffff0000, v64
	v_lshlrev_b32_e32 v62, 16, v56
	v_and_b32_e32 v63, 0xffff0000, v56
	v_lshlrev_b32_e32 v56, 16, v65
	v_lshlrev_b32_e32 v152, 16, v57
	v_and_b32_e32 v153, 0xffff0000, v57
	v_and_b32_e32 v57, 0xffff0000, v65
	v_pk_add_f32 v[54:55], v[54:55], v[62:63]
	v_mov_b64_e32 v[62:63], v[146:147]
	v_pk_add_f32 v[56:57], v[56:57], v[152:153]
	v_mov_b64_e32 v[64:65], v[148:149]

; __device__ __forceinline__ unsigned cvtpk(float lo, float hi) { f32x2_t v = {lo, hi}; bf16x2_t b = __builtin_convertvector(v, bf16x2_t); return __builtin_bit_cast(unsigned, b); }
;     __device__ __forceinline__ void operator()(const f32x4 (&acc)[2][2][4][2], const Unit& u, int wr, int wc, int fr, int fq, const float (&)[8]) const {
;         const int row0 = u.pm * 256 + wr * 64 + fr, col0 = u.pn * 256 + wc * 32 + 8 * fq;
;         float ssv[2][4];
; #pragma unroll
;         for (int ai = 0; ai < 2; ++ai)
; #pragma unroll
;             for (int m = 0; m < 4; ++m) { const int row = row0 + ai * 128 + m * 16; float ss = 0.f;
; #pragma unroll
;                 for (int bj = 0; bj < 2; ++bj) { const size_t p = (size_t)row * DM + col0 + bj * 128; const f32x4 a = acc[ai][bj][m][0], b = acc[ai][bj][m][1];
;                     u32x4 w; w.x = cvtpk(a[0], a[1]); w.y = cvtpk(a[2], a[3]); w.z = cvtpk(b[0], b[1]); w.w = cvtpk(b[2], b[3]); *(u32x4*)(HiOut + p) = w;
;                     u32x4 v; v.x = cvtpk(a[0] - bflo(w.x), a[1] - bfhi(w.x)); v.y = cvtpk(a[2] - bflo(w.y), a[3] - bfhi(w.y)); v.z = cvtpk(b[0] - bflo(w.z), b[1] - bfhi(w.z)); v.w = cvtpk(b[2] - bflo(w.w), b[3] - bfhi(w.w));
;                     *(u32x4*)(LoOut + p) = v;
;                     ss += (a[0] * a[0] + a[1] * a[1]) + (a[2] * a[2] + a[3] * a[3]) + (b[0] * b[0] + b[1] * b[1]) + (b[2] * b[2] + b[3] * b[3]); }
;                 ss += __shfl_xor(ss, 16); ss += __shfl_xor(ss, 32); ssv[ai][m] = ss; }
.LBB0_541:
	v_and_b32_e32 v144, 64, v190
	v_xor_b32_e32 v143, 16, v190
	v_add_u32_e32 v144, 64, v144
	v_cmp_lt_i32_e32 vcc, v143, v144
	v_lshl_add_u32 v142, s80, 8, v151
	v_lshl_or_b32 v148, s79, 8, v153
	v_cndmask_b32_e32 v143, v190, v143, vcc
	v_lshlrev_b32_e32 v156, 2, v143
	v_xor_b32_e32 v143, 32, v190
	v_cmp_lt_i32_e32 vcc, v143, v144
	v_ashrrev_i32_e32 v149, 31, v148
	v_cvt_pk_bf16_f32 v158, v62, v63
	v_cndmask_b32_e32 v143, v190, v143, vcc
	v_lshlrev_b32_e32 v155, 2, v143
	v_ashrrev_i32_e32 v143, 31, v142
	v_lshlrev_b64 v[144:145], 10, v[142:143]
	v_lshl_add_u64 v[144:145], v[144:145], 0, v[148:149]
	v_readlane_b32 s16, v252, 16
	v_lshlrev_b64 v[146:147], 1, v[144:145]
	v_readlane_b32 s17, v252, 17
	v_lshlrev_b32_e32 v162, 16, v158
	v_and_b32_e32 v163, 0xffff0000, v158
	v_cvt_pk_bf16_f32 v159, v64, v65
	v_cvt_pk_bf16_f32 v160, v54, v55
	v_cvt_pk_bf16_f32 v161, v56, v57
	v_lshl_add_u64 v[144:145], s[16:17], 0, v[146:147]
	v_pk_add_f32 v[162:163], v[62:63], v[162:163] neg_lo:[0,1] neg_hi:[0,1]
	global_store_dwordx4 v[144:145], v[158:161], off sc1
	v_or_b32_e32 v164, 0x100, v146
	v_mov_b32_e32 v165, v147
	v_cvt_pk_bf16_f32 v158, v162, v163
	v_lshlrev_b32_e32 v162, 16, v159
	v_and_b32_e32 v163, 0xffff0000, v159
	v_pk_add_f32 v[162:163], v[64:65], v[162:163] neg_lo:[0,1] neg_hi:[0,1]
	v_lshl_add_u64 v[164:165], s[16:17], 0, v[164:165]
	v_cvt_pk_bf16_f32 v159, v162, v163
	v_lshlrev_b32_e32 v162, 16, v160
	v_and_b32_e32 v163, 0xffff0000, v160
	v_pk_add_f32 v[162:163], v[54:55], v[162:163] neg_lo:[0,1] neg_hi:[0,1]
	s_mov_b64 s[14:15], 0x40000
	v_cvt_pk_bf16_f32 v160, v162, v163
	v_lshlrev_b32_e32 v162, 16, v161
	v_and_b32_e32 v163, 0xffff0000, v161
	v_pk_add_f32 v[162:163], v[56:57], v[162:163] neg_lo:[0,1] neg_hi:[0,1]
	s_mov_b32 s3, 0x40000
	v_cvt_pk_bf16_f32 v161, v162, v163
	v_lshl_add_u64 v[162:163], s[52:53], 0, v[146:147]
	global_store_dwordx4 v[162:163], v[158:161], off sc1
	s_nop 1
	v_cvt_pk_bf16_f32 v158, v6, v7
	v_cvt_pk_bf16_f32 v159, v8, v9
	v_cvt_pk_bf16_f32 v160, v2, v3
	v_cvt_pk_bf16_f32 v161, v4, v5
	global_store_dwordx4 v[164:165], v[158:161], off sc1
	v_lshlrev_b32_e32 v164, 16, v158
	v_and_b32_e32 v165, 0xffff0000, v158
	v_pk_add_f32 v[164:165], v[6:7], v[164:165] neg_lo:[0,1] neg_hi:[0,1]
	s_nop 0
	v_cvt_pk_bf16_f32 v158, v164, v165
	v_lshlrev_b32_e32 v164, 16, v159
	v_and_b32_e32 v165, 0xffff0000, v159
	v_pk_add_f32 v[164:165], v[8:9], v[164:165] neg_lo:[0,1] neg_hi:[0,1]
	s_nop 0
	v_cvt_pk_bf16_f32 v159, v164, v165
	v_lshlrev_b32_e32 v164, 16, v160
	v_and_b32_e32 v165, 0xffff0000, v160
	v_pk_add_f32 v[164:165], v[2:3], v[164:165] neg_lo:[0,1] neg_hi:[0,1]
	s_nop 0
	v_cvt_pk_bf16_f32 v160, v164, v165
	v_lshlrev_b32_e32 v164, 16, v161
	v_and_b32_e32 v165, 0xffff0000, v161
	v_pk_add_f32 v[164:165], v[4:5], v[164:165] neg_lo:[0,1] neg_hi:[0,1]
	s_nop 0
	v_cvt_pk_bf16_f32 v161, v164, v165
	global_store_dwordx4 v[162:163], v[158:161], off offset:256 sc1
	v_mov_b32_e32 v162, v65
	v_mov_b32_e32 v163, v9
	v_mov_b32_e32 v160, v63
	v_mov_b32_e32 v161, v7
	v_mov_b32_e32 v158, v62
	v_mov_b32_e32 v159, v6
	v_pk_mul_f32 v[160:161], v[160:161], v[160:161]
	v_pk_mul_f32 v[162:163], v[162:163], v[162:163]
	v_pk_fma_f32 v[158:159], v[158:159], v[158:159], v[160:161]
	v_mov_b32_e32 v160, v64
	v_mov_b32_e32 v161, v8
	v_pk_fma_f32 v[160:161], v[160:161], v[160:161], v[162:163]
	v_mov_b32_e32 v162, v55
	v_mov_b32_e32 v163, v3
	v_pk_add_f32 v[158:159], v[158:159], v[160:161]
	v_mov_b32_e32 v160, v54
	v_mov_b32_e32 v161, v2
	v_pk_mul_f32 v[162:163], v[162:163], v[162:163]
	s_nop 0
	v_pk_fma_f32 v[160:161], v[160:161], v[160:161], v[162:163]
	v_mov_b32_e32 v162, v57
	v_mov_b32_e32 v163, v5
	v_pk_add_f32 v[158:159], v[158:159], v[160:161]
	v_mov_b32_e32 v160, v56
	v_mov_b32_e32 v161, v4
	v_pk_mul_f32 v[162:163], v[162:163], v[162:163]
	s_nop 0
	v_pk_fma_f32 v[160:161], v[160:161], v[160:161], v[162:163]
	v_cvt_pk_bf16_f32 v162, v10, v11
	v_pk_add_f32 v[158:159], v[160:161], v[158:159]
	v_or_b32_e32 v160, 16, v142
	v_ashrrev_i32_e32 v161, 31, v160
	v_lshlrev_b64 v[160:161], 10, v[160:161]
	v_lshl_add_u64 v[164:165], v[160:161], 0, v[148:149]
	v_lshlrev_b64 v[164:165], 1, v[164:165]
	v_cvt_pk_bf16_f32 v160, v14, v15
	v_cvt_pk_bf16_f32 v161, v16, v17
	v_cvt_pk_bf16_f32 v163, v12, v13
	v_lshl_add_u64 v[166:167], s[16:17], 0, v[164:165]
	global_store_dwordx4 v[166:167], v[160:163], off sc1
	v_lshlrev_b32_e32 v166, 16, v160
	v_and_b32_e32 v167, 0xffff0000, v160
	v_pk_add_f32 v[166:167], v[14:15], v[166:167] neg_lo:[0,1] neg_hi:[0,1]
	v_add_f32_e32 v157, v158, v159
	v_cvt_pk_bf16_f32 v160, v166, v167
	v_lshlrev_b32_e32 v166, 16, v161
	v_and_b32_e32 v167, 0xffff0000, v161
	v_pk_add_f32 v[166:167], v[16:17], v[166:167] neg_lo:[0,1] neg_hi:[0,1]
	v_mul_f32_e32 v159, v15, v15
	v_cvt_pk_bf16_f32 v161, v166, v167
	v_lshlrev_b32_e32 v166, 16, v162
	v_and_b32_e32 v167, 0xffff0000, v162
	v_pk_add_f32 v[166:167], v[10:11], v[166:167] neg_lo:[0,1] neg_hi:[0,1]
	v_fmac_f32_e32 v159, v14, v14
	v_cvt_pk_bf16_f32 v162, v166, v167
	v_lshlrev_b32_e32 v166, 16, v163
	v_and_b32_e32 v167, 0xffff0000, v163
	v_pk_add_f32 v[166:167], v[12:13], v[166:167] neg_lo:[0,1] neg_hi:[0,1]
	ds_bpermute_b32 v158, v156, v157
	v_cvt_pk_bf16_f32 v163, v166, v167
	v_lshl_add_u64 v[166:167], s[52:53], 0, v[164:165]
	global_store_dwordx4 v[166:167], v[160:163], off sc1
	v_or_b32_e32 v164, 0x100, v164
	v_lshl_add_u64 v[164:165], s[16:17], 0, v[164:165]
	v_mul_f32_e32 v160, v17, v17
	v_fmac_f32_e32 v160, v16, v16
	v_add_f32_e32 v159, v159, v160
	v_mul_f32_e32 v160, v11, v11
	v_fmac_f32_e32 v160, v10, v10
	v_add_f32_e32 v159, v159, v160
	v_mul_f32_e32 v160, v13, v13
	v_fmac_f32_e32 v160, v12, v12
	v_add_f32_e32 v159, v160, v159
	v_cvt_pk_bf16_f32 v160, v22, v23
	v_cvt_pk_bf16_f32 v161, v24, v25
	v_cvt_pk_bf16_f32 v162, v18, v19
	v_cvt_pk_bf16_f32 v163, v20, v21
	global_store_dwordx4 v[164:165], v[160:163], off sc1
	v_lshlrev_b32_e32 v164, 16, v160
	v_and_b32_e32 v165, 0xffff0000, v160
	v_pk_add_f32 v[164:165], v[22:23], v[164:165] neg_lo:[0,1] neg_hi:[0,1]
	s_waitcnt lgkmcnt(0)
; __device__ __forceinline__ unsigned cvtpk(float lo, float hi) { f32x2_t v = {lo, hi}; bf16x2_t b = __builtin_convertvector(v, bf16x2_t); return __builtin_bit_cast(unsigned, b); }
;     __device__ __forceinline__ void operator()(const f32x4 (&acc)[2][2][4][2], const Unit& u, int wr, int wc, int fr, int fq, const float (&)[8]) const {
;     ...
;             for (int m = 0; m < 4; ++m) { const int row = row0 + ai * 128 + m * 16; float ss = 0.f;
; #pragma unroll
;                 for (int bj = 0; bj < 2; ++bj) { const size_t p = (size_t)row * DM + col0 + bj * 128; const f32x4 a = acc[ai][bj][m][0], b = acc[ai][bj][m][1];
;                     u32x4 w; w.x = cvtpk(a[0], a[1]); w.y = cvtpk(a[2], a[3]); w.z = cvtpk(b[0], b[1]); w.w = cvtpk(b[2], b[3]); *(u32x4*)(HiOut + p) = w;
;                     u32x4 v; v.x = cvtpk(a[0] - bflo(w.x), a[1] - bfhi(w.x)); v.y = cvtpk(a[2] - bflo(w.y), a[3] - bfhi(w.y)); v.z = cvtpk(b[0] - bflo(w.z), b[1] - bfhi(w.z)); v.w = cvtpk(b[2] - bflo(w.w), b[3] - bfhi(w.w));
;                     *(u32x4*)(LoOut + p) = v;
;                     ss += (a[0] * a[0] + a[1] * a[1]) + (a[2] * a[2] + a[3] * a[3]) + (b[0] * b[0] + b[1] * b[1]) + (b[2] * b[2] + b[3] * b[3]); }
;                 ss += __shfl_xor(ss, 16); ss += __shfl_xor(ss, 32); ssv[ai][m] = ss; }
	v_add_f32_e32 v157, v157, v158
	v_cvt_pk_bf16_f32 v160, v164, v165
	v_lshlrev_b32_e32 v164, 16, v161
	v_and_b32_e32 v165, 0xffff0000, v161
	v_pk_add_f32 v[164:165], v[24:25], v[164:165] neg_lo:[0,1] neg_hi:[0,1]
	ds_bpermute_b32 v158, v155, v157
	v_cvt_pk_bf16_f32 v161, v164, v165
	v_lshlrev_b32_e32 v164, 16, v162
	v_and_b32_e32 v165, 0xffff0000, v162
	v_pk_add_f32 v[164:165], v[18:19], v[164:165] neg_lo:[0,1] neg_hi:[0,1]
	s_nop 0
	v_cvt_pk_bf16_f32 v162, v164, v165
	v_lshlrev_b32_e32 v164, 16, v163
	v_and_b32_e32 v165, 0xffff0000, v163
	v_pk_add_f32 v[164:165], v[20:21], v[164:165] neg_lo:[0,1] neg_hi:[0,1]
	s_nop 0
	v_cvt_pk_bf16_f32 v163, v164, v165
	global_store_dwordx4 v[166:167], v[160:163], off offset:256 sc1
	v_cvt_pk_bf16_f32 v164, v26, v27
	v_cvt_pk_bf16_f32 v165, v28, v29
	v_or_b32_e32 v162, 32, v142
	v_ashrrev_i32_e32 v163, 31, v162
	v_lshlrev_b64 v[162:163], 10, v[162:163]
	v_lshl_add_u64 v[166:167], v[162:163], 0, v[148:149]
	v_lshlrev_b64 v[166:167], 1, v[166:167]
	v_cvt_pk_bf16_f32 v162, v30, v31
	v_cvt_pk_bf16_f32 v163, v32, v33
	v_lshl_add_u64 v[168:169], s[16:17], 0, v[166:167]
	global_store_dwordx4 v[168:169], v[162:165], off sc1
	v_lshlrev_b32_e32 v168, 16, v162
	v_and_b32_e32 v169, 0xffff0000, v162
	v_pk_add_f32 v[168:169], v[30:31], v[168:169] neg_lo:[0,1] neg_hi:[0,1]
	v_mul_f32_e32 v160, v23, v23
	v_cvt_pk_bf16_f32 v162, v168, v169
	v_lshlrev_b32_e32 v168, 16, v163
	v_and_b32_e32 v169, 0xffff0000, v163
	v_mul_f32_e32 v161, v25, v25
	v_pk_add_f32 v[168:169], v[32:33], v[168:169] neg_lo:[0,1] neg_hi:[0,1]
	v_fmac_f32_e32 v160, v22, v22
	v_fmac_f32_e32 v161, v24, v24
	v_cvt_pk_bf16_f32 v163, v168, v169
	v_lshlrev_b32_e32 v168, 16, v164
	v_and_b32_e32 v169, 0xffff0000, v164
	v_add_f32_e32 v160, v160, v161
	v_mul_f32_e32 v161, v19, v19
	v_pk_add_f32 v[168:169], v[26:27], v[168:169] neg_lo:[0,1] neg_hi:[0,1]
	v_fmac_f32_e32 v161, v18, v18
	v_cvt_pk_bf16_f32 v164, v168, v169
	v_lshlrev_b32_e32 v168, 16, v165
	v_and_b32_e32 v169, 0xffff0000, v165
	v_add_f32_e32 v160, v160, v161
	v_mul_f32_e32 v161, v21, v21
	v_pk_add_f32 v[168:169], v[28:29], v[168:169] neg_lo:[0,1] neg_hi:[0,1]
	v_fmac_f32_e32 v161, v20, v20
	v_cvt_pk_bf16_f32 v165, v168, v169
	v_lshl_add_u64 v[168:169], s[52:53], 0, v[166:167]
	v_add_f32_e32 v160, v161, v160
	global_store_dwordx4 v[168:169], v[162:165], off sc1
	v_mul_f32_e32 v161, v31, v31
	v_fmac_f32_e32 v161, v30, v30
	v_mul_f32_e32 v162, v33, v33
	v_fmac_f32_e32 v162, v32, v32
	v_add_f32_e32 v161, v161, v162
	v_mul_f32_e32 v162, v27, v27
	v_fmac_f32_e32 v162, v26, v26
	v_add_f32_e32 v161, v161, v162
	v_mul_f32_e32 v162, v29, v29
	v_fmac_f32_e32 v162, v28, v28
	v_or_b32_e32 v166, 0x100, v166
	v_add_f32_e32 v161, v162, v161
	v_cvt_pk_bf16_f32 v162, v38, v39
	v_cvt_pk_bf16_f32 v163, v40, v41
	v_cvt_pk_bf16_f32 v164, v34, v35
	v_cvt_pk_bf16_f32 v165, v36, v37
	v_lshl_add_u64 v[166:167], s[16:17], 0, v[166:167]
	global_store_dwordx4 v[166:167], v[162:165], off sc1
	v_lshlrev_b32_e32 v166, 16, v162
	v_and_b32_e32 v167, 0xffff0000, v162
	v_pk_add_f32 v[166:167], v[38:39], v[166:167] neg_lo:[0,1] neg_hi:[0,1]
	v_add_f32_e32 v159, v159, v160
	v_cvt_pk_bf16_f32 v162, v166, v167
	v_lshlrev_b32_e32 v166, 16, v163
	v_and_b32_e32 v167, 0xffff0000, v163
	v_pk_add_f32 v[166:167], v[40:41], v[166:167] neg_lo:[0,1] neg_hi:[0,1]
	ds_bpermute_b32 v160, v156, v159
	v_cvt_pk_bf16_f32 v163, v166, v167
	v_lshlrev_b32_e32 v166, 16, v164
	v_and_b32_e32 v167, 0xffff0000, v164
	v_pk_add_f32 v[166:167], v[34:35], v[166:167] neg_lo:[0,1] neg_hi:[0,1]
	s_waitcnt lgkmcnt(0)
	v_add_f32_e32 v159, v159, v160
	v_cvt_pk_bf16_f32 v164, v166, v167
	v_lshlrev_b32_e32 v166, 16, v165
	v_and_b32_e32 v167, 0xffff0000, v165
	v_pk_add_f32 v[166:167], v[36:37], v[166:167] neg_lo:[0,1] neg_hi:[0,1]
	ds_bpermute_b32 v160, v155, v159
	v_cvt_pk_bf16_f32 v165, v166, v167
	global_store_dwordx4 v[168:169], v[162:165], off offset:256 sc1
	v_cvt_pk_bf16_f32 v166, v42, v43
	v_cvt_pk_bf16_f32 v167, v44, v45
	v_or_b32_e32 v164, 48, v142
	v_ashrrev_i32_e32 v165, 31, v164
	v_lshlrev_b64 v[164:165], 10, v[164:165]
	v_lshl_add_u64 v[148:149], v[164:165], 0, v[148:149]
	v_lshlrev_b64 v[148:149], 1, v[148:149]
	v_cvt_pk_bf16_f32 v164, v46, v47
	v_cvt_pk_bf16_f32 v165, v48, v49
	v_lshl_add_u64 v[168:169], s[16:17], 0, v[148:149]
	global_store_dwordx4 v[168:169], v[164:167], off sc1
	v_lshlrev_b32_e32 v168, 16, v164
	v_and_b32_e32 v169, 0xffff0000, v164
	v_pk_add_f32 v[168:169], v[46:47], v[168:169] neg_lo:[0,1] neg_hi:[0,1]
	v_mul_f32_e32 v162, v39, v39
	v_cvt_pk_bf16_f32 v164, v168, v169
	v_lshlrev_b32_e32 v168, 16, v165
	v_and_b32_e32 v169, 0xffff0000, v165
	v_mul_f32_e32 v163, v41, v41
	v_pk_add_f32 v[168:169], v[48:49], v[168:169] neg_lo:[0,1] neg_hi:[0,1]
	v_fmac_f32_e32 v162, v38, v38
	v_fmac_f32_e32 v163, v40, v40
	v_cvt_pk_bf16_f32 v165, v168, v169
	v_lshlrev_b32_e32 v168, 16, v166
	v_and_b32_e32 v169, 0xffff0000, v166
	v_add_f32_e32 v162, v162, v163
	v_mul_f32_e32 v163, v35, v35
	v_pk_add_f32 v[168:169], v[42:43], v[168:169] neg_lo:[0,1] neg_hi:[0,1]
	v_fmac_f32_e32 v163, v34, v34
	v_cvt_pk_bf16_f32 v166, v168, v169
	v_lshlrev_b32_e32 v168, 16, v167
	v_and_b32_e32 v169, 0xffff0000, v167
	v_add_f32_e32 v162, v162, v163
	v_mul_f32_e32 v163, v37, v37
	v_pk_add_f32 v[168:169], v[44:45], v[168:169] neg_lo:[0,1] neg_hi:[0,1]
	v_fmac_f32_e32 v163, v36, v36
	v_cvt_pk_bf16_f32 v167, v168, v169
	v_lshl_add_u64 v[168:169], s[52:53], 0, v[148:149]
	v_add_f32_e32 v162, v163, v162
	global_store_dwordx4 v[168:169], v[164:167], off sc1
	v_mul_f32_e32 v163, v47, v47
	v_fmac_f32_e32 v163, v46, v46
	v_mul_f32_e32 v164, v49, v49
	v_fmac_f32_e32 v164, v48, v48
	v_add_f32_e32 v163, v163, v164
	v_mul_f32_e32 v164, v43, v43
	v_fmac_f32_e32 v164, v42, v42
	v_add_f32_e32 v163, v163, v164
	v_mul_f32_e32 v164, v45, v45
	v_fmac_f32_e32 v164, v44, v44
	v_or_b32_e32 v148, 0x100, v148
	v_add_f32_e32 v163, v164, v163
	v_cvt_pk_bf16_f32 v164, v58, v59
	v_cvt_pk_bf16_f32 v165, v60, v61
	v_cvt_pk_bf16_f32 v166, v50, v51
	v_cvt_pk_bf16_f32 v167, v52, v53
	v_lshl_add_u64 v[148:149], s[16:17], 0, v[148:149]
	global_store_dwordx4 v[148:149], v[164:167], off sc1
	v_lshlrev_b32_e32 v148, 16, v164
	v_and_b32_e32 v149, 0xffff0000, v164
	v_pk_add_f32 v[148:149], v[58:59], v[148:149] neg_lo:[0,1] neg_hi:[0,1]
	v_add_f32_e32 v161, v161, v162
	v_cvt_pk_bf16_f32 v164, v148, v149
	v_lshlrev_b32_e32 v148, 16, v165
	v_and_b32_e32 v149, 0xffff0000, v165
	v_pk_add_f32 v[148:149], v[60:61], v[148:149] neg_lo:[0,1] neg_hi:[0,1]
	ds_bpermute_b32 v162, v156, v161
	v_cvt_pk_bf16_f32 v165, v148, v149
	v_lshlrev_b32_e32 v148, 16, v166
	v_and_b32_e32 v149, 0xffff0000, v166
	v_pk_add_f32 v[148:149], v[50:51], v[148:149] neg_lo:[0,1] neg_hi:[0,1]
	s_waitcnt lgkmcnt(0)
; __device__ __forceinline__ unsigned cvtpk(float lo, float hi) { f32x2_t v = {lo, hi}; bf16x2_t b = __builtin_convertvector(v, bf16x2_t); return __builtin_bit_cast(unsigned, b); }
;     __device__ __forceinline__ void operator()(const f32x4 (&acc)[2][2][4][2], const Unit& u, int wr, int wc, int fr, int fq, const float (&)[8]) const {
;     ...
;             for (int m = 0; m < 4; ++m) { const int row = row0 + ai * 128 + m * 16; float ss = 0.f;
; #pragma unroll
;                 for (int bj = 0; bj < 2; ++bj) { const size_t p = (size_t)row * DM + col0 + bj * 128; const f32x4 a = acc[ai][bj][m][0], b = acc[ai][bj][m][1];
;                     u32x4 w; w.x = cvtpk(a[0], a[1]); w.y = cvtpk(a[2], a[3]); w.z = cvtpk(b[0], b[1]); w.w = cvtpk(b[2], b[3]); *(u32x4*)(HiOut + p) = w;
;                     u32x4 v; v.x = cvtpk(a[0] - bflo(w.x), a[1] - bfhi(w.x)); v.y = cvtpk(a[2] - bflo(w.y), a[3] - bfhi(w.y)); v.z = cvtpk(b[0] - bflo(w.z), b[1] - bfhi(w.z)); v.w = cvtpk(b[2] - bflo(w.w), b[3] - bfhi(w.w));
;                     *(u32x4*)(LoOut + p) = v;
;                     ss += (a[0] * a[0] + a[1] * a[1]) + (a[2] * a[2] + a[3] * a[3]) + (b[0] * b[0] + b[1] * b[1]) + (b[2] * b[2] + b[3] * b[3]); }
;                 ss += __shfl_xor(ss, 16); ss += __shfl_xor(ss, 32); ssv[ai][m] = ss; }
	v_add_f32_e32 v161, v161, v162
	v_cvt_pk_bf16_f32 v166, v148, v149
	v_lshlrev_b32_e32 v148, 16, v167
	v_and_b32_e32 v149, 0xffff0000, v167
	v_pk_add_f32 v[148:149], v[52:53], v[148:149] neg_lo:[0,1] neg_hi:[0,1]
	ds_bpermute_b32 v162, v155, v161
	v_cvt_pk_bf16_f32 v167, v148, v149
	global_store_dwordx4 v[168:169], v[164:167], off offset:256 sc1
	v_lshl_add_u64 v[168:169], v[146:147], 0, s[14:15]
	v_lshl_add_u64 v[170:171], s[16:17], 0, v[168:169]
	v_cvt_pk_bf16_f32 v164, v70, v71
	v_cvt_pk_bf16_f32 v165, v72, v73
	v_cvt_pk_bf16_f32 v166, v66, v67
	v_cvt_pk_bf16_f32 v167, v68, v69
	global_store_dwordx4 v[170:171], v[164:167], off sc1
	v_lshlrev_b32_e32 v170, 16, v164
	v_and_b32_e32 v171, 0xffff0000, v164
	v_pk_add_f32 v[170:171], v[70:71], v[170:171] neg_lo:[0,1] neg_hi:[0,1]
	v_mul_f32_e32 v148, v59, v59
	v_mul_f32_e32 v149, v61, v61
	v_cvt_pk_bf16_f32 v164, v170, v171
	v_lshlrev_b32_e32 v170, 16, v165
	v_and_b32_e32 v171, 0xffff0000, v165
	v_fmac_f32_e32 v148, v58, v58
	v_fmac_f32_e32 v149, v60, v60
	v_pk_add_f32 v[170:171], v[72:73], v[170:171] neg_lo:[0,1] neg_hi:[0,1]
	v_add_f32_e32 v148, v148, v149
	v_mul_f32_e32 v149, v51, v51
	v_cvt_pk_bf16_f32 v165, v170, v171
	v_lshlrev_b32_e32 v170, 16, v166
	v_and_b32_e32 v171, 0xffff0000, v166
	v_fmac_f32_e32 v149, v50, v50
	v_pk_add_f32 v[170:171], v[66:67], v[170:171] neg_lo:[0,1] neg_hi:[0,1]
	v_add_f32_e32 v148, v148, v149
	v_mul_f32_e32 v149, v53, v53
	v_cvt_pk_bf16_f32 v166, v170, v171
	v_lshlrev_b32_e32 v170, 16, v167
	v_and_b32_e32 v171, 0xffff0000, v167
	v_fmac_f32_e32 v149, v52, v52
	v_pk_add_f32 v[170:171], v[68:69], v[170:171] neg_lo:[0,1] neg_hi:[0,1]
	v_add_f32_e32 v148, v149, v148
	v_cvt_pk_bf16_f32 v167, v170, v171
	v_lshl_add_u64 v[168:169], s[52:53], 0, v[168:169]
	v_add_f32_e32 v148, v163, v148
	global_store_dwordx4 v[168:169], v[164:167], off sc1
	v_mul_f32_e32 v163, v71, v71
	v_fmac_f32_e32 v163, v70, v70
	v_mul_f32_e32 v164, v73, v73
	v_fmac_f32_e32 v164, v72, v72
	v_add_f32_e32 v163, v163, v164
	v_mul_f32_e32 v164, v67, v67
	v_fmac_f32_e32 v164, v66, v66
	v_add_f32_e32 v163, v163, v164
	v_mul_f32_e32 v164, v69, v69
	v_fmac_f32_e32 v164, v68, v68
	v_add_co_u32_e32 v170, vcc, s3, v144
	v_add_f32_e32 v163, v164, v163
	v_cvt_pk_bf16_f32 v164, v78, v79
	v_cvt_pk_bf16_f32 v165, v80, v81
	v_cvt_pk_bf16_f32 v166, v74, v75
	v_cvt_pk_bf16_f32 v167, v76, v77
	v_addc_co_u32_e32 v171, vcc, 0, v145, vcc
	global_store_dwordx4 v[170:171], v[164:167], off offset:256 sc1
	v_lshlrev_b32_e32 v170, 16, v164
	v_and_b32_e32 v171, 0xffff0000, v164
	v_pk_add_f32 v[170:171], v[78:79], v[170:171] neg_lo:[0,1] neg_hi:[0,1]
	s_mov_b64 s[14:15], 0x48000
	v_cvt_pk_bf16_f32 v164, v170, v171
	v_lshlrev_b32_e32 v170, 16, v165
	v_and_b32_e32 v171, 0xffff0000, v165
	v_pk_add_f32 v[170:171], v[80:81], v[170:171] neg_lo:[0,1] neg_hi:[0,1]
	s_mov_b32 s3, 0x48000
	v_cvt_pk_bf16_f32 v165, v170, v171
	v_lshlrev_b32_e32 v170, 16, v166
	v_and_b32_e32 v171, 0xffff0000, v166
	v_pk_add_f32 v[170:171], v[74:75], v[170:171] neg_lo:[0,1] neg_hi:[0,1]
	ds_bpermute_b32 v149, v156, v148
	v_cvt_pk_bf16_f32 v166, v170, v171
	v_lshlrev_b32_e32 v170, 16, v167
	v_and_b32_e32 v171, 0xffff0000, v167
	v_pk_add_f32 v[170:171], v[76:77], v[170:171] neg_lo:[0,1] neg_hi:[0,1]
	s_waitcnt lgkmcnt(0)
	v_add_f32_e32 v148, v148, v149
	v_cvt_pk_bf16_f32 v167, v170, v171
	v_lshl_add_u64 v[170:171], v[146:147], 0, s[14:15]
	global_store_dwordx4 v[168:169], v[164:167], off offset:256 sc1
	v_cvt_pk_bf16_f32 v168, v82, v83
	v_cvt_pk_bf16_f32 v169, v84, v85
	v_cvt_pk_bf16_f32 v166, v86, v87
	v_cvt_pk_bf16_f32 v167, v88, v89
	v_lshl_add_u64 v[172:173], s[16:17], 0, v[170:171]
	global_store_dwordx4 v[172:173], v[166:169], off sc1
	v_lshlrev_b32_e32 v172, 16, v166
	v_and_b32_e32 v173, 0xffff0000, v166
	v_pk_add_f32 v[172:173], v[86:87], v[172:173] neg_lo:[0,1] neg_hi:[0,1]
	v_mul_f32_e32 v164, v79, v79
	v_cvt_pk_bf16_f32 v166, v172, v173
	v_lshlrev_b32_e32 v172, 16, v167
	v_and_b32_e32 v173, 0xffff0000, v167
	v_mul_f32_e32 v165, v81, v81
	v_pk_add_f32 v[172:173], v[88:89], v[172:173] neg_lo:[0,1] neg_hi:[0,1]
	v_fmac_f32_e32 v164, v78, v78
	v_fmac_f32_e32 v165, v80, v80
	v_cvt_pk_bf16_f32 v167, v172, v173
	v_lshlrev_b32_e32 v172, 16, v168
	v_and_b32_e32 v173, 0xffff0000, v168
	v_add_f32_e32 v164, v164, v165
	v_mul_f32_e32 v165, v75, v75
	v_pk_add_f32 v[172:173], v[82:83], v[172:173] neg_lo:[0,1] neg_hi:[0,1]
	v_fmac_f32_e32 v165, v74, v74
	v_cvt_pk_bf16_f32 v168, v172, v173
	v_lshlrev_b32_e32 v172, 16, v169
	v_and_b32_e32 v173, 0xffff0000, v169
	v_add_f32_e32 v164, v164, v165
	v_mul_f32_e32 v165, v77, v77
	v_pk_add_f32 v[172:173], v[84:85], v[172:173] neg_lo:[0,1] neg_hi:[0,1]
	v_fmac_f32_e32 v165, v76, v76
	v_cvt_pk_bf16_f32 v169, v172, v173
	v_lshl_add_u64 v[170:171], s[52:53], 0, v[170:171]
	v_add_f32_e32 v164, v165, v164
	global_store_dwordx4 v[170:171], v[166:169], off sc1
	v_mul_f32_e32 v165, v87, v87
	v_fmac_f32_e32 v165, v86, v86
	v_mul_f32_e32 v166, v89, v89
	v_fmac_f32_e32 v166, v88, v88
	v_add_f32_e32 v165, v165, v166
	v_mul_f32_e32 v166, v83, v83
	v_fmac_f32_e32 v166, v82, v82
	v_add_f32_e32 v165, v165, v166
	v_mul_f32_e32 v166, v85, v85
	v_fmac_f32_e32 v166, v84, v84
	v_add_co_u32_e32 v172, vcc, s3, v144
	v_add_f32_e32 v165, v166, v165
	v_cvt_pk_bf16_f32 v166, v94, v95
	v_cvt_pk_bf16_f32 v167, v96, v97
	v_cvt_pk_bf16_f32 v168, v90, v91
	v_cvt_pk_bf16_f32 v169, v92, v93
	v_addc_co_u32_e32 v173, vcc, 0, v145, vcc
	global_store_dwordx4 v[172:173], v[166:169], off offset:256 sc1
	v_lshlrev_b32_e32 v172, 16, v166
	v_and_b32_e32 v173, 0xffff0000, v166
	v_pk_add_f32 v[172:173], v[94:95], v[172:173] neg_lo:[0,1] neg_hi:[0,1]
; __device__ __forceinline__ unsigned cvtpk(float lo, float hi) { f32x2_t v = {lo, hi}; bf16x2_t b = __builtin_convertvector(v, bf16x2_t); return __builtin_bit_cast(unsigned, b); }
;     __device__ __forceinline__ void operator()(const f32x4 (&acc)[2][2][4][2], const Unit& u, int wr, int wc, int fr, int fq, const float (&)[8]) const {
;     ...
;             for (int m = 0; m < 4; ++m) { const int row = row0 + ai * 128 + m * 16; float ss = 0.f;
; #pragma unroll
;                 for (int bj = 0; bj < 2; ++bj) { const size_t p = (size_t)row * DM + col0 + bj * 128; const f32x4 a = acc[ai][bj][m][0], b = acc[ai][bj][m][1];
;                     u32x4 w; w.x = cvtpk(a[0], a[1]); w.y = cvtpk(a[2], a[3]); w.z = cvtpk(b[0], b[1]); w.w = cvtpk(b[2], b[3]); *(u32x4*)(HiOut + p) = w;
;                     u32x4 v; v.x = cvtpk(a[0] - bflo(w.x), a[1] - bfhi(w.x)); v.y = cvtpk(a[2] - bflo(w.y), a[3] - bfhi(w.y)); v.z = cvtpk(b[0] - bflo(w.z), b[1] - bfhi(w.z)); v.w = cvtpk(b[2] - bflo(w.w), b[3] - bfhi(w.w));
;                     *(u32x4*)(LoOut + p) = v;
;                     ss += (a[0] * a[0] + a[1] * a[1]) + (a[2] * a[2] + a[3] * a[3]) + (b[0] * b[0] + b[1] * b[1]) + (b[2] * b[2] + b[3] * b[3]); }
;                 ss += __shfl_xor(ss, 16); ss += __shfl_xor(ss, 32); ssv[ai][m] = ss; }
	s_mov_b64 s[14:15], 0x50000
	v_cvt_pk_bf16_f32 v166, v172, v173
	v_lshlrev_b32_e32 v172, 16, v167
	v_and_b32_e32 v173, 0xffff0000, v167
	v_pk_add_f32 v[172:173], v[96:97], v[172:173] neg_lo:[0,1] neg_hi:[0,1]
	s_mov_b32 s3, 0x50000
	v_cvt_pk_bf16_f32 v167, v172, v173
	v_lshlrev_b32_e32 v172, 16, v168
	v_and_b32_e32 v173, 0xffff0000, v168
	v_pk_add_f32 v[172:173], v[90:91], v[172:173] neg_lo:[0,1] neg_hi:[0,1]
	v_add_f32_e32 v163, v163, v164
	v_cvt_pk_bf16_f32 v168, v172, v173
	v_lshlrev_b32_e32 v172, 16, v169
	v_and_b32_e32 v173, 0xffff0000, v169
	v_pk_add_f32 v[172:173], v[92:93], v[172:173] neg_lo:[0,1] neg_hi:[0,1]
	ds_bpermute_b32 v164, v156, v163
	v_cvt_pk_bf16_f32 v169, v172, v173
	v_lshl_add_u64 v[172:173], v[146:147], 0, s[14:15]
	global_store_dwordx4 v[170:171], v[166:169], off offset:256 sc1
	v_cvt_pk_bf16_f32 v170, v98, v99
	v_cvt_pk_bf16_f32 v171, v100, v101
	v_cvt_pk_bf16_f32 v168, v102, v103
	v_cvt_pk_bf16_f32 v169, v104, v105
	v_lshl_add_u64 v[174:175], s[16:17], 0, v[172:173]
	global_store_dwordx4 v[174:175], v[168:171], off sc1
	v_lshlrev_b32_e32 v174, 16, v168
	v_and_b32_e32 v175, 0xffff0000, v168
	v_pk_add_f32 v[174:175], v[102:103], v[174:175] neg_lo:[0,1] neg_hi:[0,1]
	v_mul_f32_e32 v166, v95, v95
	v_cvt_pk_bf16_f32 v168, v174, v175
	v_lshlrev_b32_e32 v174, 16, v169
	v_and_b32_e32 v175, 0xffff0000, v169
	v_mul_f32_e32 v167, v97, v97
	v_pk_add_f32 v[174:175], v[104:105], v[174:175] neg_lo:[0,1] neg_hi:[0,1]
	v_fmac_f32_e32 v166, v94, v94
	v_fmac_f32_e32 v167, v96, v96
	v_cvt_pk_bf16_f32 v169, v174, v175
	v_lshlrev_b32_e32 v174, 16, v170
	v_and_b32_e32 v175, 0xffff0000, v170
	v_add_f32_e32 v166, v166, v167
	v_mul_f32_e32 v167, v91, v91
	v_pk_add_f32 v[174:175], v[98:99], v[174:175] neg_lo:[0,1] neg_hi:[0,1]
	v_fmac_f32_e32 v167, v90, v90
	v_cvt_pk_bf16_f32 v170, v174, v175
	v_lshlrev_b32_e32 v174, 16, v171
	v_and_b32_e32 v175, 0xffff0000, v171
	v_add_f32_e32 v166, v166, v167
	v_mul_f32_e32 v167, v93, v93
	v_pk_add_f32 v[174:175], v[100:101], v[174:175] neg_lo:[0,1] neg_hi:[0,1]
	v_fmac_f32_e32 v167, v92, v92
	v_cvt_pk_bf16_f32 v171, v174, v175
	v_lshl_add_u64 v[172:173], s[52:53], 0, v[172:173]
	v_add_f32_e32 v166, v167, v166
	global_store_dwordx4 v[172:173], v[168:171], off sc1
	v_mul_f32_e32 v167, v103, v103
	v_fmac_f32_e32 v167, v102, v102
	v_mul_f32_e32 v168, v105, v105
	v_fmac_f32_e32 v168, v104, v104
	v_add_f32_e32 v167, v167, v168
	v_mul_f32_e32 v168, v99, v99
	v_fmac_f32_e32 v168, v98, v98
	v_add_f32_e32 v167, v167, v168
	v_mul_f32_e32 v168, v101, v101
	v_fmac_f32_e32 v168, v100, v100
	v_add_co_u32_e32 v174, vcc, s3, v144
	v_add_f32_e32 v167, v168, v167
	v_cvt_pk_bf16_f32 v168, v110, v111
	v_cvt_pk_bf16_f32 v169, v112, v113
	v_cvt_pk_bf16_f32 v170, v106, v107
	v_cvt_pk_bf16_f32 v171, v108, v109
	v_addc_co_u32_e32 v175, vcc, 0, v145, vcc
	global_store_dwordx4 v[174:175], v[168:171], off offset:256 sc1
	v_lshlrev_b32_e32 v174, 16, v168
	v_and_b32_e32 v175, 0xffff0000, v168
	v_pk_add_f32 v[174:175], v[110:111], v[174:175] neg_lo:[0,1] neg_hi:[0,1]
	s_mov_b64 s[14:15], 0x58000
	v_cvt_pk_bf16_f32 v168, v174, v175
	v_lshlrev_b32_e32 v174, 16, v169
	v_and_b32_e32 v175, 0xffff0000, v169
	v_pk_add_f32 v[174:175], v[112:113], v[174:175] neg_lo:[0,1] neg_hi:[0,1]
	v_lshl_add_u64 v[146:147], v[146:147], 0, s[14:15]
	v_cvt_pk_bf16_f32 v169, v174, v175
	v_lshlrev_b32_e32 v174, 16, v170
	v_and_b32_e32 v175, 0xffff0000, v170
	v_pk_add_f32 v[174:175], v[106:107], v[174:175] neg_lo:[0,1] neg_hi:[0,1]
	s_mov_b32 s3, 0x58000
	v_cvt_pk_bf16_f32 v170, v174, v175
	v_lshlrev_b32_e32 v174, 16, v171
	v_and_b32_e32 v175, 0xffff0000, v171
	v_pk_add_f32 v[174:175], v[108:109], v[174:175] neg_lo:[0,1] neg_hi:[0,1]
	v_add_co_u32_e32 v144, vcc, s3, v144
	v_cvt_pk_bf16_f32 v171, v174, v175
	global_store_dwordx4 v[172:173], v[168:171], off offset:256 sc1
	v_cvt_pk_bf16_f32 v172, v114, v115
	v_cvt_pk_bf16_f32 v173, v116, v117
	v_cvt_pk_bf16_f32 v170, v118, v119
	v_cvt_pk_bf16_f32 v171, v120, v121
; __device__ __forceinline__ unsigned cvtpk(float lo, float hi) { f32x2_t v = {lo, hi}; bf16x2_t b = __builtin_convertvector(v, bf16x2_t); return __builtin_bit_cast(unsigned, b); }
;     __device__ __forceinline__ void operator()(const f32x4 (&acc)[2][2][4][2], const Unit& u, int wr, int wc, int fr, int fq, const float (&)[8]) const {
;     ...
;             for (int m = 0; m < 4; ++m) { const int row = row0 + ai * 128 + m * 16; float ss = 0.f;
; #pragma unroll
;                 for (int bj = 0; bj < 2; ++bj) { const size_t p = (size_t)row * DM + col0 + bj * 128; const f32x4 a = acc[ai][bj][m][0], b = acc[ai][bj][m][1];
;                     u32x4 w; w.x = cvtpk(a[0], a[1]); w.y = cvtpk(a[2], a[3]); w.z = cvtpk(b[0], b[1]); w.w = cvtpk(b[2], b[3]); *(u32x4*)(HiOut + p) = w;
;                     u32x4 v; v.x = cvtpk(a[0] - bflo(w.x), a[1] - bfhi(w.x)); v.y = cvtpk(a[2] - bflo(w.y), a[3] - bfhi(w.y)); v.z = cvtpk(b[0] - bflo(w.z), b[1] - bfhi(w.z)); v.w = cvtpk(b[2] - bflo(w.w), b[3] - bfhi(w.w));
;                     *(u32x4*)(LoOut + p) = v;
;                     ss += (a[0] * a[0] + a[1] * a[1]) + (a[2] * a[2] + a[3] * a[3]) + (b[0] * b[0] + b[1] * b[1]) + (b[2] * b[2] + b[3] * b[3]); }
;                 ss += __shfl_xor(ss, 16); ss += __shfl_xor(ss, 32); ssv[ai][m] = ss; }
; #pragma unroll
;         for (int ai = 0; ai < 2; ++ai) { const float v = fq == 0 ? ssv[ai][0] : fq == 1 ? ssv[ai][1] : fq == 2 ? ssv[ai][2] : ssv[ai][3];
;             (void)__hip_atomic_fetch_add(RS + row0 + ai * 128 + fq * 16, v, __ATOMIC_RELAXED, __HIP_MEMORY_SCOPE_AGENT); }
	v_lshl_add_u64 v[174:175], s[16:17], 0, v[146:147]
	global_store_dwordx4 v[174:175], v[170:173], off sc1
	v_lshlrev_b32_e32 v174, 16, v170
	v_and_b32_e32 v175, 0xffff0000, v170
	v_pk_add_f32 v[174:175], v[118:119], v[174:175] neg_lo:[0,1] neg_hi:[0,1]
	v_mul_f32_e32 v168, v111, v111
	v_cvt_pk_bf16_f32 v170, v174, v175
	v_lshlrev_b32_e32 v174, 16, v171
	v_and_b32_e32 v175, 0xffff0000, v171
	v_pk_add_f32 v[174:175], v[120:121], v[174:175] neg_lo:[0,1] neg_hi:[0,1]
	v_mul_f32_e32 v169, v113, v113
	v_cvt_pk_bf16_f32 v171, v174, v175
	v_lshlrev_b32_e32 v174, 16, v172
	v_and_b32_e32 v175, 0xffff0000, v172
	v_pk_add_f32 v[174:175], v[114:115], v[174:175] neg_lo:[0,1] neg_hi:[0,1]
	v_fmac_f32_e32 v168, v110, v110
	v_cvt_pk_bf16_f32 v172, v174, v175
	v_lshlrev_b32_e32 v174, 16, v173
	v_and_b32_e32 v175, 0xffff0000, v173
	v_pk_add_f32 v[174:175], v[116:117], v[174:175] neg_lo:[0,1] neg_hi:[0,1]
	v_fmac_f32_e32 v169, v112, v112
	v_cvt_pk_bf16_f32 v173, v174, v175
	v_lshl_add_u64 v[174:175], s[52:53], 0, v[146:147]
	v_mul_f32_e32 v146, v119, v119
	v_mul_f32_e32 v147, v121, v121
	v_fmac_f32_e32 v146, v118, v118
	v_fmac_f32_e32 v147, v120, v120
	v_add_f32_e32 v168, v168, v169
	v_mul_f32_e32 v169, v107, v107
	v_add_f32_e32 v146, v146, v147
	v_mul_f32_e32 v147, v115, v115
	v_fmac_f32_e32 v169, v106, v106
	v_fmac_f32_e32 v147, v114, v114
	v_add_f32_e32 v168, v168, v169
	v_mul_f32_e32 v169, v109, v109
	v_add_f32_e32 v146, v146, v147
	v_mul_f32_e32 v147, v117, v117
	v_fmac_f32_e32 v169, v108, v108
	global_store_dwordx4 v[174:175], v[170:173], off sc1
	v_fmac_f32_e32 v147, v116, v116
	v_addc_co_u32_e32 v145, vcc, 0, v145, vcc
	v_cvt_pk_bf16_f32 v170, v126, v127
	v_cvt_pk_bf16_f32 v171, v128, v129
	v_cvt_pk_bf16_f32 v172, v122, v123
	v_cvt_pk_bf16_f32 v173, v124, v125
	v_add_f32_e32 v168, v169, v168
	v_add_f32_e32 v169, v147, v146
	global_store_dwordx4 v[144:145], v[170:173], off offset:256 sc1
	v_lshlrev_b32_e32 v144, 16, v170
	v_and_b32_e32 v145, 0xffff0000, v170
	v_lshlrev_b32_e32 v146, 16, v171
	v_and_b32_e32 v147, 0xffff0000, v171
	v_pk_add_f32 v[144:145], v[126:127], v[144:145] neg_lo:[0,1] neg_hi:[0,1]
	v_pk_add_f32 v[146:147], v[128:129], v[146:147] neg_lo:[0,1] neg_hi:[0,1]
	v_cvt_pk_bf16_f32 v144, v144, v145
	v_cvt_pk_bf16_f32 v145, v146, v147
	v_lshlrev_b32_e32 v146, 16, v172
	v_and_b32_e32 v147, 0xffff0000, v172
	v_lshlrev_b32_e32 v170, 16, v173
	v_and_b32_e32 v171, 0xffff0000, v173
	v_pk_add_f32 v[146:147], v[122:123], v[146:147] neg_lo:[0,1] neg_hi:[0,1]
	v_pk_add_f32 v[170:171], v[124:125], v[170:171] neg_lo:[0,1] neg_hi:[0,1]
	v_cvt_pk_bf16_f32 v146, v146, v147
	v_cvt_pk_bf16_f32 v147, v170, v171
	global_store_dwordx4 v[174:175], v[144:147], off offset:256 sc1
	v_add_f32_e32 v165, v165, v166
	v_add_f32_e32 v167, v167, v168
	v_mul_f32_e32 v144, v127, v127
	v_mul_f32_e32 v145, v129, v129
	v_fmac_f32_e32 v144, v126, v126
	v_fmac_f32_e32 v145, v128, v128
	v_add_f32_e32 v144, v144, v145
	v_mul_f32_e32 v145, v123, v123
	v_fmac_f32_e32 v145, v122, v122
	v_add_f32_e32 v144, v144, v145
	v_mul_f32_e32 v145, v125, v125
	v_fmac_f32_e32 v145, v124, v124
	v_add_f32_e32 v144, v145, v144
	v_add_f32_e32 v144, v169, v144
	ds_bpermute_b32 v166, v156, v165
	ds_bpermute_b32 v168, v156, v167
	ds_bpermute_b32 v145, v156, v144
	s_waitcnt lgkmcnt(0)
	v_add_f32_e32 v163, v163, v164
	ds_bpermute_b32 v149, v155, v148
	v_add_f32_e32 v165, v165, v166
	v_add_f32_e32 v167, v167, v168
	v_add_f32_e32 v144, v144, v145
	ds_bpermute_b32 v164, v155, v163
	ds_bpermute_b32 v166, v155, v165
	ds_bpermute_b32 v168, v155, v167
	ds_bpermute_b32 v145, v155, v144
	v_cmp_lt_i32_e32 vcc, 1, v150
	s_and_saveexec_b64 s[14:15], vcc
	s_xor_b64 s[16:17], exec, s[14:15]
	s_cbranch_execz .LBB0_547
	v_cmp_lt_i32_e32 vcc, 2, v150
	s_and_saveexec_b64 s[14:15], vcc
	s_xor_b64 s[18:19], exec, s[14:15]
	s_andn2_saveexec_b64 s[18:19], s[18:19]
	s_cbranch_execz .LBB0_546
	v_mov_b32_e32 v148, v161
	s_waitcnt lgkmcnt(0)
	v_mov_b32_e32 v149, v162
